# v7: LDS K-fragment reads issued before the tile's ds_writes in both attention loops; softmax VALU trims; top-k reload loads batched
# baseline (speedup 1.0000x reference)
; DI void topk_group(const Params& p, int t, char* smem, unsigned* scr1, unsigned* scr2, unsigned* scr3) {
;     ...
;   for (int qi = 1; qi < NQ; ++qi) {
;     const unsigned* scr = qi == 1 ? scr1 : (qi == 2 ? scr2 : scr3);
;     __syncthreads();
;     *(int4*)&hist[tid * 8] = make_int4(0, 0, 0, 0);
;     *(int4*)&hist[tid * 8 + 4] = make_int4(0, 0, 0, 0);
;     __syncthreads();
;     for (int i = tid * 4; i < n; i += 256 * 4) {
;       const u32x4 u4 = *(const u32x4*)(scr + i);
;       *(u32x4*)(sc + i) = u4;
; #pragma unroll
;       for (int e = 0; e < 4; ++e) atomicAdd(&hist[u4[e] >> 21], 1);
;     }
.LBB0_1462:
	s_mov_b32 s41, s40
	s_mov_b32 s42, s40
	s_mov_b32 s43, s40
	v_mov_b64_e32 v[0:1], s[40:41]
	v_mov_b64_e32 v[2:3], s[42:43]
	s_barrier
	ds_write_b128 v207, v[0:3]
	ds_write_b128 v207, v[0:3] offset:16
	s_waitcnt lgkmcnt(0)
	s_barrier
	s_and_saveexec_b64 s[0:1], s[20:21]
	s_cbranch_execz .LBB0_1465
	s_cmp_eq_u32 s33, 1
	s_cselect_b64 vcc, -1, 0
	s_cmp_eq_u32 s33, 2
	s_cselect_b64 s[24:25], -1, 0
	v_cndmask_b32_e64 v0, v176, v174, s[24:25]
	v_cndmask_b32_e64 v1, v177, v175, s[24:25]
	v_cndmask_b32_e32 v1, v1, v173, vcc
	v_cndmask_b32_e32 v0, v0, v172, vcc
	v_lshl_add_u64 v[0:1], v[0:1], 0, v[10:11]
	s_mov_b64 s[24:25], 0
	v_mov_b32_e32 v2, v26
	v_mov_b32_e32 v3, v16
	s_mov_b64 s[26:27], 0x1000
	global_load_dwordx4 v[40:43], v[0:1], off
	v_add_u32_e32 v3, 0x400, v3
	v_cmp_ge_i32_e32 vcc, v3, v206
	v_lshl_add_u64 v[0:1], v[0:1], 0, s[26:27]
	s_or_b64 s[24:25], vcc, s[24:25]
	s_andn2_b64 exec, exec, s[24:25]
	s_cbranch_execz .Lrl_issued
	global_load_dwordx4 v[44:47], v[0:1], off
	v_add_u32_e32 v3, 0x400, v3
	v_cmp_ge_i32_e32 vcc, v3, v206
	v_lshl_add_u64 v[0:1], v[0:1], 0, s[26:27]
	s_or_b64 s[24:25], vcc, s[24:25]
	s_andn2_b64 exec, exec, s[24:25]
	s_cbranch_execz .Lrl_issued
	global_load_dwordx4 v[48:51], v[0:1], off
	v_add_u32_e32 v3, 0x400, v3
	v_cmp_ge_i32_e32 vcc, v3, v206
	v_lshl_add_u64 v[0:1], v[0:1], 0, s[26:27]
	s_or_b64 s[24:25], vcc, s[24:25]
	s_andn2_b64 exec, exec, s[24:25]
	s_cbranch_execz .Lrl_issued
	global_load_dwordx4 v[52:55], v[0:1], off
	v_add_u32_e32 v3, 0x400, v3
	v_cmp_ge_i32_e32 vcc, v3, v206
	v_lshl_add_u64 v[0:1], v[0:1], 0, s[26:27]
	s_or_b64 s[24:25], vcc, s[24:25]
	s_andn2_b64 exec, exec, s[24:25]
	s_cbranch_execz .Lrl_issued
	global_load_dwordx4 v[56:59], v[0:1], off
	v_add_u32_e32 v3, 0x400, v3
	v_cmp_ge_i32_e32 vcc, v3, v206
	v_lshl_add_u64 v[0:1], v[0:1], 0, s[26:27]
	s_or_b64 s[24:25], vcc, s[24:25]
	s_andn2_b64 exec, exec, s[24:25]
	s_cbranch_execz .Lrl_issued
	global_load_dwordx4 v[60:63], v[0:1], off
	v_add_u32_e32 v3, 0x400, v3
	v_cmp_ge_i32_e32 vcc, v3, v206
	v_lshl_add_u64 v[0:1], v[0:1], 0, s[26:27]
	s_or_b64 s[24:25], vcc, s[24:25]
	s_andn2_b64 exec, exec, s[24:25]
	s_cbranch_execz .Lrl_issued
	global_load_dwordx4 v[64:67], v[0:1], off
	v_add_u32_e32 v3, 0x400, v3
	v_cmp_ge_i32_e32 vcc, v3, v206
	v_lshl_add_u64 v[0:1], v[0:1], 0, s[26:27]
	s_or_b64 s[24:25], vcc, s[24:25]
	s_andn2_b64 exec, exec, s[24:25]
	s_cbranch_execz .Lrl_issued
	global_load_dwordx4 v[68:71], v[0:1], off
	v_add_u32_e32 v3, 0x400, v3
	v_cmp_ge_i32_e32 vcc, v3, v206
	v_lshl_add_u64 v[0:1], v[0:1], 0, s[26:27]
	s_or_b64 s[24:25], vcc, s[24:25]
	s_andn2_b64 exec, exec, s[24:25]
	s_cbranch_execz .Lrl_issued
	global_load_dwordx4 v[72:75], v[0:1], off
	v_add_u32_e32 v3, 0x400, v3
	v_cmp_ge_i32_e32 vcc, v3, v206
	v_lshl_add_u64 v[0:1], v[0:1], 0, s[26:27]
	s_or_b64 s[24:25], vcc, s[24:25]
	s_andn2_b64 exec, exec, s[24:25]
	s_cbranch_execz .Lrl_issued
	global_load_dwordx4 v[76:79], v[0:1], off
	v_add_u32_e32 v3, 0x400, v3
	v_cmp_ge_i32_e32 vcc, v3, v206
	v_lshl_add_u64 v[0:1], v[0:1], 0, s[26:27]
	s_or_b64 s[24:25], vcc, s[24:25]
	s_andn2_b64 exec, exec, s[24:25]
	s_cbranch_execz .Lrl_issued
	global_load_dwordx4 v[80:83], v[0:1], off
	v_add_u32_e32 v3, 0x400, v3
	v_cmp_ge_i32_e32 vcc, v3, v206
	v_lshl_add_u64 v[0:1], v[0:1], 0, s[26:27]
	s_or_b64 s[24:25], vcc, s[24:25]
	s_andn2_b64 exec, exec, s[24:25]
	s_cbranch_execz .Lrl_issued
	global_load_dwordx4 v[84:87], v[0:1], off
	v_add_u32_e32 v3, 0x400, v3
	v_cmp_ge_i32_e32 vcc, v3, v206
	v_lshl_add_u64 v[0:1], v[0:1], 0, s[26:27]
	s_or_b64 s[24:25], vcc, s[24:25]
	s_andn2_b64 exec, exec, s[24:25]
	s_cbranch_execz .Lrl_issued
	global_load_dwordx4 v[88:91], v[0:1], off
	v_add_u32_e32 v3, 0x400, v3
	v_cmp_ge_i32_e32 vcc, v3, v206
	v_lshl_add_u64 v[0:1], v[0:1], 0, s[26:27]
	s_or_b64 s[24:25], vcc, s[24:25]
	s_andn2_b64 exec, exec, s[24:25]
	s_cbranch_execz .Lrl_issued
	global_load_dwordx4 v[92:95], v[0:1], off
	v_add_u32_e32 v3, 0x400, v3
	v_cmp_ge_i32_e32 vcc, v3, v206
	v_lshl_add_u64 v[0:1], v[0:1], 0, s[26:27]
	s_or_b64 s[24:25], vcc, s[24:25]
	s_andn2_b64 exec, exec, s[24:25]
	s_cbranch_execz .Lrl_issued
	global_load_dwordx4 v[96:99], v[0:1], off
	v_add_u32_e32 v3, 0x400, v3
	v_cmp_ge_i32_e32 vcc, v3, v206
	v_lshl_add_u64 v[0:1], v[0:1], 0, s[26:27]
	s_or_b64 s[24:25], vcc, s[24:25]
	s_andn2_b64 exec, exec, s[24:25]
	s_cbranch_execz .Lrl_issued
	global_load_dwordx4 v[100:103], v[0:1], off
	v_add_u32_e32 v3, 0x400, v3
	v_cmp_ge_i32_e32 vcc, v3, v206
	v_lshl_add_u64 v[0:1], v[0:1], 0, s[26:27]
	s_or_b64 s[24:25], vcc, s[24:25]
	s_andn2_b64 exec, exec, s[24:25]
; DI void topk_group(const Params& p, int t, char* smem, unsigned* scr1, unsigned* scr2, unsigned* scr3) {
;     ...
;     for (int i = tid * 4; i < n; i += 256 * 4) {
;       const u32x4 u4 = *(const u32x4*)(scr + i);
;       *(u32x4*)(sc + i) = u4;
; #pragma unroll
;       for (int e = 0; e < 4; ++e) atomicAdd(&hist[u4[e] >> 21], 1);
;     }
.Lrl_issued:
	s_and_b64 exec, s[0:1], s[20:21]
	s_mov_b64 s[24:25], 0
	v_mov_b32_e32 v3, v16
	s_waitcnt vmcnt(0)
	ds_write_b128 v2, v[40:43]
	v_lshrrev_b32_e32 v40, 19, v40
	v_lshrrev_b32_e32 v41, 19, v41
	v_lshrrev_b32_e32 v42, 19, v42
	v_lshrrev_b32_e32 v43, 19, v43
	v_and_b32_e32 v40, 0x1ffc, v40
	v_and_b32_e32 v41, 0x1ffc, v41
	v_and_b32_e32 v42, 0x1ffc, v42
	v_and_b32_e32 v43, 0x1ffc, v43
	v_add_u32_e32 v40, v197, v40
	v_add_u32_e32 v41, v197, v41
	v_add_u32_e32 v42, v197, v42
	v_add_u32_e32 v43, v197, v43
	ds_add_u32 v40, v202
	ds_add_u32 v41, v202
	ds_add_u32 v42, v202
	ds_add_u32 v43, v202
	v_add_u32_e32 v3, 0x400, v3
	v_cmp_ge_i32_e32 vcc, v3, v206
	v_add_u32_e32 v2, 0x1000, v2
	s_or_b64 s[24:25], vcc, s[24:25]
	s_andn2_b64 exec, exec, s[24:25]
	s_cbranch_execz .Lrl_done
	ds_write_b128 v2, v[44:47]
	v_lshrrev_b32_e32 v44, 19, v44
	v_lshrrev_b32_e32 v45, 19, v45
	v_lshrrev_b32_e32 v46, 19, v46
	v_lshrrev_b32_e32 v47, 19, v47
	v_and_b32_e32 v44, 0x1ffc, v44
	v_and_b32_e32 v45, 0x1ffc, v45
	v_and_b32_e32 v46, 0x1ffc, v46
	v_and_b32_e32 v47, 0x1ffc, v47
	v_add_u32_e32 v44, v197, v44
	v_add_u32_e32 v45, v197, v45
	v_add_u32_e32 v46, v197, v46
	v_add_u32_e32 v47, v197, v47
	ds_add_u32 v44, v202
	ds_add_u32 v45, v202
	ds_add_u32 v46, v202
	ds_add_u32 v47, v202
	v_add_u32_e32 v3, 0x400, v3
	v_cmp_ge_i32_e32 vcc, v3, v206
	v_add_u32_e32 v2, 0x1000, v2
	s_or_b64 s[24:25], vcc, s[24:25]
	s_andn2_b64 exec, exec, s[24:25]
	s_cbranch_execz .Lrl_done
	ds_write_b128 v2, v[48:51]
	v_lshrrev_b32_e32 v48, 19, v48
	v_lshrrev_b32_e32 v49, 19, v49
	v_lshrrev_b32_e32 v50, 19, v50
	v_lshrrev_b32_e32 v51, 19, v51
	v_and_b32_e32 v48, 0x1ffc, v48
	v_and_b32_e32 v49, 0x1ffc, v49
	v_and_b32_e32 v50, 0x1ffc, v50
	v_and_b32_e32 v51, 0x1ffc, v51
	v_add_u32_e32 v48, v197, v48
	v_add_u32_e32 v49, v197, v49
	v_add_u32_e32 v50, v197, v50
	v_add_u32_e32 v51, v197, v51
	ds_add_u32 v48, v202
	ds_add_u32 v49, v202
	ds_add_u32 v50, v202
	ds_add_u32 v51, v202
	v_add_u32_e32 v3, 0x400, v3
	v_cmp_ge_i32_e32 vcc, v3, v206
	v_add_u32_e32 v2, 0x1000, v2
	s_or_b64 s[24:25], vcc, s[24:25]
	s_andn2_b64 exec, exec, s[24:25]
	s_cbranch_execz .Lrl_done
	ds_write_b128 v2, v[52:55]
	v_lshrrev_b32_e32 v52, 19, v52
	v_lshrrev_b32_e32 v53, 19, v53
	v_lshrrev_b32_e32 v54, 19, v54
	v_lshrrev_b32_e32 v55, 19, v55
	v_and_b32_e32 v52, 0x1ffc, v52
	v_and_b32_e32 v53, 0x1ffc, v53
	v_and_b32_e32 v54, 0x1ffc, v54
	v_and_b32_e32 v55, 0x1ffc, v55
	v_add_u32_e32 v52, v197, v52
	v_add_u32_e32 v53, v197, v53
	v_add_u32_e32 v54, v197, v54
	v_add_u32_e32 v55, v197, v55
	ds_add_u32 v52, v202
	ds_add_u32 v53, v202
	ds_add_u32 v54, v202
	ds_add_u32 v55, v202
	v_add_u32_e32 v3, 0x400, v3
	v_cmp_ge_i32_e32 vcc, v3, v206
	v_add_u32_e32 v2, 0x1000, v2
	s_or_b64 s[24:25], vcc, s[24:25]
	s_andn2_b64 exec, exec, s[24:25]
	s_cbranch_execz .Lrl_done
	ds_write_b128 v2, v[56:59]
	v_lshrrev_b32_e32 v56, 19, v56
	v_lshrrev_b32_e32 v57, 19, v57
	v_lshrrev_b32_e32 v58, 19, v58
	v_lshrrev_b32_e32 v59, 19, v59
	v_and_b32_e32 v56, 0x1ffc, v56
	v_and_b32_e32 v57, 0x1ffc, v57
	v_and_b32_e32 v58, 0x1ffc, v58
	v_and_b32_e32 v59, 0x1ffc, v59
	v_add_u32_e32 v56, v197, v56
	v_add_u32_e32 v57, v197, v57
	v_add_u32_e32 v58, v197, v58
	v_add_u32_e32 v59, v197, v59
	ds_add_u32 v56, v202
	ds_add_u32 v57, v202
	ds_add_u32 v58, v202
	ds_add_u32 v59, v202
	v_add_u32_e32 v3, 0x400, v3
	v_cmp_ge_i32_e32 vcc, v3, v206
	v_add_u32_e32 v2, 0x1000, v2
	s_or_b64 s[24:25], vcc, s[24:25]
	s_andn2_b64 exec, exec, s[24:25]
	s_cbranch_execz .Lrl_done
	ds_write_b128 v2, v[60:63]
	v_lshrrev_b32_e32 v60, 19, v60
	v_lshrrev_b32_e32 v61, 19, v61
	v_lshrrev_b32_e32 v62, 19, v62
	v_lshrrev_b32_e32 v63, 19, v63
	v_and_b32_e32 v60, 0x1ffc, v60
	v_and_b32_e32 v61, 0x1ffc, v61
	v_and_b32_e32 v62, 0x1ffc, v62
	v_and_b32_e32 v63, 0x1ffc, v63
	v_add_u32_e32 v60, v197, v60
	v_add_u32_e32 v61, v197, v61
	v_add_u32_e32 v62, v197, v62
	v_add_u32_e32 v63, v197, v63
	ds_add_u32 v60, v202
	ds_add_u32 v61, v202
	ds_add_u32 v62, v202
	ds_add_u32 v63, v202
	v_add_u32_e32 v3, 0x400, v3
	v_cmp_ge_i32_e32 vcc, v3, v206
	v_add_u32_e32 v2, 0x1000, v2
	s_or_b64 s[24:25], vcc, s[24:25]
	s_andn2_b64 exec, exec, s[24:25]
	s_cbranch_execz .Lrl_done
	ds_write_b128 v2, v[64:67]
	v_lshrrev_b32_e32 v64, 19, v64
	v_lshrrev_b32_e32 v65, 19, v65
	v_lshrrev_b32_e32 v66, 19, v66
	v_lshrrev_b32_e32 v67, 19, v67
	v_and_b32_e32 v64, 0x1ffc, v64
	v_and_b32_e32 v65, 0x1ffc, v65
	v_and_b32_e32 v66, 0x1ffc, v66
	v_and_b32_e32 v67, 0x1ffc, v67
	v_add_u32_e32 v64, v197, v64
	v_add_u32_e32 v65, v197, v65
	v_add_u32_e32 v66, v197, v66
	v_add_u32_e32 v67, v197, v67
	ds_add_u32 v64, v202
	ds_add_u32 v65, v202
	ds_add_u32 v66, v202
	ds_add_u32 v67, v202
	v_add_u32_e32 v3, 0x400, v3
	v_cmp_ge_i32_e32 vcc, v3, v206
	v_add_u32_e32 v2, 0x1000, v2
	s_or_b64 s[24:25], vcc, s[24:25]
	s_andn2_b64 exec, exec, s[24:25]
	s_cbranch_execz .Lrl_done
	ds_write_b128 v2, v[68:71]
	v_lshrrev_b32_e32 v68, 19, v68
	v_lshrrev_b32_e32 v69, 19, v69
	v_lshrrev_b32_e32 v70, 19, v70
	v_lshrrev_b32_e32 v71, 19, v71
	v_and_b32_e32 v68, 0x1ffc, v68
	v_and_b32_e32 v69, 0x1ffc, v69
	v_and_b32_e32 v70, 0x1ffc, v70
	v_and_b32_e32 v71, 0x1ffc, v71
	v_add_u32_e32 v68, v197, v68
	v_add_u32_e32 v69, v197, v69
	v_add_u32_e32 v70, v197, v70
	v_add_u32_e32 v71, v197, v71
	ds_add_u32 v68, v202
	ds_add_u32 v69, v202
	ds_add_u32 v70, v202
	ds_add_u32 v71, v202
	v_add_u32_e32 v3, 0x400, v3
	v_cmp_ge_i32_e32 vcc, v3, v206
	v_add_u32_e32 v2, 0x1000, v2
	s_or_b64 s[24:25], vcc, s[24:25]
	s_andn2_b64 exec, exec, s[24:25]
	s_cbranch_execz .Lrl_done
; DI void topk_group(const Params& p, int t, char* smem, unsigned* scr1, unsigned* scr2, unsigned* scr3) {
;     ...
;     for (int i = tid * 4; i < n; i += 256 * 4) {
;       const u32x4 u4 = *(const u32x4*)(scr + i);
;       *(u32x4*)(sc + i) = u4;
; #pragma unroll
;       for (int e = 0; e < 4; ++e) atomicAdd(&hist[u4[e] >> 21], 1);
;     }
	ds_write_b128 v2, v[72:75]
	v_lshrrev_b32_e32 v72, 19, v72
	v_lshrrev_b32_e32 v73, 19, v73
	v_lshrrev_b32_e32 v74, 19, v74
	v_lshrrev_b32_e32 v75, 19, v75
	v_and_b32_e32 v72, 0x1ffc, v72
	v_and_b32_e32 v73, 0x1ffc, v73
	v_and_b32_e32 v74, 0x1ffc, v74
	v_and_b32_e32 v75, 0x1ffc, v75
	v_add_u32_e32 v72, v197, v72
	v_add_u32_e32 v73, v197, v73
	v_add_u32_e32 v74, v197, v74
	v_add_u32_e32 v75, v197, v75
	ds_add_u32 v72, v202
	ds_add_u32 v73, v202
	ds_add_u32 v74, v202
	ds_add_u32 v75, v202
	v_add_u32_e32 v3, 0x400, v3
	v_cmp_ge_i32_e32 vcc, v3, v206
	v_add_u32_e32 v2, 0x1000, v2
	s_or_b64 s[24:25], vcc, s[24:25]
	s_andn2_b64 exec, exec, s[24:25]
	s_cbranch_execz .Lrl_done
	ds_write_b128 v2, v[76:79]
	v_lshrrev_b32_e32 v76, 19, v76
	v_lshrrev_b32_e32 v77, 19, v77
	v_lshrrev_b32_e32 v78, 19, v78
	v_lshrrev_b32_e32 v79, 19, v79
	v_and_b32_e32 v76, 0x1ffc, v76
	v_and_b32_e32 v77, 0x1ffc, v77
	v_and_b32_e32 v78, 0x1ffc, v78
	v_and_b32_e32 v79, 0x1ffc, v79
	v_add_u32_e32 v76, v197, v76
	v_add_u32_e32 v77, v197, v77
	v_add_u32_e32 v78, v197, v78
	v_add_u32_e32 v79, v197, v79
	ds_add_u32 v76, v202
	ds_add_u32 v77, v202
	ds_add_u32 v78, v202
	ds_add_u32 v79, v202
	v_add_u32_e32 v3, 0x400, v3
	v_cmp_ge_i32_e32 vcc, v3, v206
	v_add_u32_e32 v2, 0x1000, v2
	s_or_b64 s[24:25], vcc, s[24:25]
	s_andn2_b64 exec, exec, s[24:25]
	s_cbranch_execz .Lrl_done
	ds_write_b128 v2, v[80:83]
	v_lshrrev_b32_e32 v80, 19, v80
	v_lshrrev_b32_e32 v81, 19, v81
	v_lshrrev_b32_e32 v82, 19, v82
	v_lshrrev_b32_e32 v83, 19, v83
	v_and_b32_e32 v80, 0x1ffc, v80
	v_and_b32_e32 v81, 0x1ffc, v81
	v_and_b32_e32 v82, 0x1ffc, v82
	v_and_b32_e32 v83, 0x1ffc, v83
	v_add_u32_e32 v80, v197, v80
	v_add_u32_e32 v81, v197, v81
	v_add_u32_e32 v82, v197, v82
	v_add_u32_e32 v83, v197, v83
	ds_add_u32 v80, v202
	ds_add_u32 v81, v202
	ds_add_u32 v82, v202
	ds_add_u32 v83, v202
	v_add_u32_e32 v3, 0x400, v3
	v_cmp_ge_i32_e32 vcc, v3, v206
	v_add_u32_e32 v2, 0x1000, v2
	s_or_b64 s[24:25], vcc, s[24:25]
	s_andn2_b64 exec, exec, s[24:25]
	s_cbranch_execz .Lrl_done
	ds_write_b128 v2, v[84:87]
	v_lshrrev_b32_e32 v84, 19, v84
	v_lshrrev_b32_e32 v85, 19, v85
	v_lshrrev_b32_e32 v86, 19, v86
	v_lshrrev_b32_e32 v87, 19, v87
	v_and_b32_e32 v84, 0x1ffc, v84
	v_and_b32_e32 v85, 0x1ffc, v85
	v_and_b32_e32 v86, 0x1ffc, v86
	v_and_b32_e32 v87, 0x1ffc, v87
	v_add_u32_e32 v84, v197, v84
	v_add_u32_e32 v85, v197, v85
	v_add_u32_e32 v86, v197, v86
	v_add_u32_e32 v87, v197, v87
	ds_add_u32 v84, v202
	ds_add_u32 v85, v202
	ds_add_u32 v86, v202
	ds_add_u32 v87, v202
	v_add_u32_e32 v3, 0x400, v3
	v_cmp_ge_i32_e32 vcc, v3, v206
	v_add_u32_e32 v2, 0x1000, v2
	s_or_b64 s[24:25], vcc, s[24:25]
	s_andn2_b64 exec, exec, s[24:25]
	s_cbranch_execz .Lrl_done
	ds_write_b128 v2, v[88:91]
	v_lshrrev_b32_e32 v88, 19, v88
	v_lshrrev_b32_e32 v89, 19, v89
	v_lshrrev_b32_e32 v90, 19, v90
	v_lshrrev_b32_e32 v91, 19, v91
	v_and_b32_e32 v88, 0x1ffc, v88
	v_and_b32_e32 v89, 0x1ffc, v89
	v_and_b32_e32 v90, 0x1ffc, v90
	v_and_b32_e32 v91, 0x1ffc, v91
	v_add_u32_e32 v88, v197, v88
	v_add_u32_e32 v89, v197, v89
	v_add_u32_e32 v90, v197, v90
	v_add_u32_e32 v91, v197, v91
	ds_add_u32 v88, v202
	ds_add_u32 v89, v202
	ds_add_u32 v90, v202
	ds_add_u32 v91, v202
	v_add_u32_e32 v3, 0x400, v3
	v_cmp_ge_i32_e32 vcc, v3, v206
	v_add_u32_e32 v2, 0x1000, v2
	s_or_b64 s[24:25], vcc, s[24:25]
	s_andn2_b64 exec, exec, s[24:25]
	s_cbranch_execz .Lrl_done
	ds_write_b128 v2, v[92:95]
	v_lshrrev_b32_e32 v92, 19, v92
	v_lshrrev_b32_e32 v93, 19, v93
	v_lshrrev_b32_e32 v94, 19, v94
	v_lshrrev_b32_e32 v95, 19, v95
	v_and_b32_e32 v92, 0x1ffc, v92
	v_and_b32_e32 v93, 0x1ffc, v93
	v_and_b32_e32 v94, 0x1ffc, v94
	v_and_b32_e32 v95, 0x1ffc, v95
	v_add_u32_e32 v92, v197, v92
	v_add_u32_e32 v93, v197, v93
	v_add_u32_e32 v94, v197, v94
	v_add_u32_e32 v95, v197, v95
	ds_add_u32 v92, v202
	ds_add_u32 v93, v202
	ds_add_u32 v94, v202
	ds_add_u32 v95, v202
	v_add_u32_e32 v3, 0x400, v3
	v_cmp_ge_i32_e32 vcc, v3, v206
	v_add_u32_e32 v2, 0x1000, v2
	s_or_b64 s[24:25], vcc, s[24:25]
	s_andn2_b64 exec, exec, s[24:25]
	s_cbranch_execz .Lrl_done
	ds_write_b128 v2, v[96:99]
	v_lshrrev_b32_e32 v96, 19, v96
	v_lshrrev_b32_e32 v97, 19, v97
	v_lshrrev_b32_e32 v98, 19, v98
	v_lshrrev_b32_e32 v99, 19, v99
	v_and_b32_e32 v96, 0x1ffc, v96
	v_and_b32_e32 v97, 0x1ffc, v97
	v_and_b32_e32 v98, 0x1ffc, v98
	v_and_b32_e32 v99, 0x1ffc, v99
	v_add_u32_e32 v96, v197, v96
	v_add_u32_e32 v97, v197, v97
	v_add_u32_e32 v98, v197, v98
	v_add_u32_e32 v99, v197, v99
	ds_add_u32 v96, v202
	ds_add_u32 v97, v202
	ds_add_u32 v98, v202
	ds_add_u32 v99, v202
	v_add_u32_e32 v3, 0x400, v3
	v_cmp_ge_i32_e32 vcc, v3, v206
	v_add_u32_e32 v2, 0x1000, v2
	s_or_b64 s[24:25], vcc, s[24:25]
	s_andn2_b64 exec, exec, s[24:25]
	s_cbranch_execz .Lrl_done
	ds_write_b128 v2, v[100:103]
	v_lshrrev_b32_e32 v100, 19, v100
	v_lshrrev_b32_e32 v101, 19, v101
	v_lshrrev_b32_e32 v102, 19, v102
	v_lshrrev_b32_e32 v103, 19, v103
	v_and_b32_e32 v100, 0x1ffc, v100
	v_and_b32_e32 v101, 0x1ffc, v101
	v_and_b32_e32 v102, 0x1ffc, v102
	v_and_b32_e32 v103, 0x1ffc, v103
	v_add_u32_e32 v100, v197, v100
	v_add_u32_e32 v101, v197, v101
	v_add_u32_e32 v102, v197, v102
	v_add_u32_e32 v103, v197, v103
	ds_add_u32 v100, v202
	ds_add_u32 v101, v202
	ds_add_u32 v102, v202
	ds_add_u32 v103, v202
	v_add_u32_e32 v3, 0x400, v3
	v_cmp_ge_i32_e32 vcc, v3, v206
	v_add_u32_e32 v2, 0x1000, v2
	s_or_b64 s[24:25], vcc, s[24:25]
	s_andn2_b64 exec, exec, s[24:25]
.Lrl_done:
.LBB0_1465:
	s_or_b64 exec, exec, s[0:1]
	v_mov_b32_e32 v187, v185
	s_mov_b64 s[0:1], 0
	v_mov_b32_e32 v33, 0
	s_mov_b32 s34, 0
	v_mov_b64_e32 v[14:15], v[186:187]
	s_waitcnt lgkmcnt(0)
	s_barrier
	s_branch .LBB0_1467

; template <int MODE>
; DI void attn_item(const Params& p, int item, char* smem, u16* gdst) {
;     ...
;   for (int jt = 0; jt < ntiles; ++jt) {
;     const int key0 = jt * 64;
;     u16* sK = sbase + (jt & 1) * ASTAGE;
;     u16* sV = sK + 64 * KSTR;
;     unsigned long long mq[2] = {mqn[0], mqn[1]};
;     if (MODE == 1) {
;       const int jn = min(jt + 1, ntiles - 1);
; #pragma unroll
;       for (int qt = 0; qt < 2; ++qt) mqn[qt] = p.SEL[(size_t)(q0 + qrow[qt]) * 256 + jn];
;     }
;     __syncthreads();
;     if (!direct) {
;       if (jt + 1 < ntiles) KV_STORE((jt + 1) & 1)
;       KV_LOAD(min(jt + 2, ntiles - 1))
;     ...
;       for (int kt = 0; kt < 4; ++kt) {
; #pragma unroll
;         for (int ks = 0; ks < NKS; ++ks) {
;           bf16x8 kf = *(const bf16x8*)(sK + (kt * 16 + fr) * KSTR + (ks >> 1) * 64 + ((ks & 1) ? ko1 : ko0));
.LBB0_1564:
	s_bitcmp1_b32 s4, 0
	s_cselect_b32 s5, 0xa800, 0
	s_add_i32 s21, s4, 1
	s_min_i32 s0, s21, s11
	s_ashr_i32 s1, s0, 31
	s_lshl_b64 s[0:1], s[0:1], 3
	s_add_u32 s0, s72, s0
	s_addc_u32 s1, s73, s1
	v_lshl_add_u64 v[96:97], s[0:1], 0, v[148:149]
	v_lshl_add_u64 v[98:99], s[0:1], 0, v[150:151]
	global_load_dwordx2 v[160:161], v[96:97], off
	global_load_dwordx2 v[162:163], v[98:99], off
	s_mov_b64 s[0:1], -1
	s_and_b64 vcc, exec, s[8:9]
	s_waitcnt lgkmcnt(0)
	s_barrier
	s_cbranch_vccz .LBB0_1573
	s_add_i32 s60, s5, 0
	v_add_u32_e32 v168, s60, v197
	v_add_u32_e32 v128, v168, v196
	v_add_u32_e32 v129, v168, v198
	ds_read_b128 v[232:235], v128
	ds_read_b128 v[236:239], v129
	ds_read_b128 v[240:243], v128 offset:128
	ds_read_b128 v[244:247], v129 offset:128
	v_add_u32_e32 v132, s60, v199
	v_add_u32_e32 v136, v132, v196
	v_add_u32_e32 v137, v132, v198
	ds_read_b128 v[248:251], v136
	s_cmp_ge_i32 s21, s51
	s_cbranch_scc1 .LBB0_1567
	s_bitcmp1_b32 s21, 0
	s_cselect_b32 s0, 0xa800, 0
	s_add_i32 s0, s0, 0
	v_add3_u32 v97, s0, v188, v187
	v_add3_u32 v96, s0, v189, v204
	s_waitcnt vmcnt(5)
	ds_write_b128 v97, v[112:115]
	s_waitcnt vmcnt(4)
	ds_write_b128 v97, v[116:119] offset:12288
	s_waitcnt vmcnt(3)
	ds_write_b128 v96, v[120:123] offset:24576
	s_waitcnt vmcnt(2)
	ds_write_b128 v96, v[124:127] offset:33792
.LBB0_1567:
	s_waitcnt vmcnt(2)
	s_add_i32 s0, s4, 2
	s_min_i32 s0, s0, s11
	s_lshl_b32 s0, s0, 6
	s_add_i32 s16, s0, s10
	s_ashr_i32 s17, s16, 31
	v_lshl_add_u64 v[96:97], v[152:153], 0, s[16:17]
	v_lshlrev_b64 v[96:97], 12, v[96:97]
	v_lshl_add_u64 v[96:97], v[158:159], 0, v[96:97]
	v_add_co_u32_e32 v100, vcc, 0x20000, v96
	s_ashr_i32 s1, s0, 31
	s_nop 0
	v_addc_co_u32_e32 v101, vcc, 0, v97, vcc
	global_load_dwordx4 v[96:99], v[96:97], off
	s_nop 0
	global_load_dwordx4 v[104:107], v[100:101], off
	v_lshl_add_u64 v[100:101], s[0:1], 1, v[154:155]
	v_lshl_add_u64 v[108:109], v[100:101], 0, s[14:15]
	global_load_dwordx4 v[100:103], v[100:101], off
	s_nop 0
	global_load_dwordx4 v[108:111], v[108:109], off
	s_lshl_b32 s61, s4, 6
	v_cmp_lt_i32_e32 vcc, s4, v182
	s_and_b64 s[0:1], s[2:3], vcc
	s_and_saveexec_b64 s[16:17], s[0:1]
	s_cbranch_execz .LBB0_1577
	s_branch .Ldsa_qk_main

; template <int MODE>
; DI void attn_item(const Params& p, int item, char* smem, u16* gdst) {
;     ...
;       for (int kt = 0; kt < 4; ++kt) {
; #pragma unroll
;         for (int ks = 0; ks < NKS; ++ks) {
;           bf16x8 kf = *(const bf16x8*)(sK + (kt * 16 + fr) * KSTR + (ks >> 1) * 64 + ((ks & 1) ? ko1 : ko0));
.LBB0_1569:
	s_waitcnt vmcnt(6)
	v_add_u32_e32 v168, s60, v197
	v_add_u32_e32 v128, v168, v196
	v_add_u32_e32 v129, v168, v198
	ds_read_b128 v[232:235], v128
	ds_read_b128 v[236:239], v129
	ds_read_b128 v[240:243], v128 offset:128
	ds_read_b128 v[244:247], v129 offset:128
	v_add_u32_e32 v132, s60, v199
	v_add_u32_e32 v136, v132, v196
	v_add_u32_e32 v137, v132, v198
	ds_read_b128 v[248:251], v136

; DI float xq_max(float x) {
;   auto a = __builtin_amdgcn_permlane16_swap(__float_as_uint(x), __float_as_uint(x), false, false);
;   x = fmaxf(__uint_as_float(a[0]), __uint_as_float(a[1]));
;   auto b = __builtin_amdgcn_permlane32_swap(__float_as_uint(x), __float_as_uint(x), false, false);
;   return fmaxf(__uint_as_float(b[0]), __uint_as_float(b[1]));
; }
; template <int MODE>
; DI void attn_item(const Params& p, int item, char* smem, u16* gdst) {
;     ...
;         float mx = -1e30f;
; #pragma unroll
;         for (int kt = 0; kt < 4; ++kt)
; #pragma unroll
;           for (int j = 0; j < 4; ++j) mx = fmaxf(mx, s[qt][kt][j]);
;         mx = xq_max(mx);
;         const float delta = (jt == 0) ? mx : fmaxf(mx, 0.f);
;         mrow[qt] = (jt == 0) ? delta : mrow[qt] + delta;
;         const bool grow = __ballot(delta != 0.f) != 0ull;
;         float alpha = 1.f;
;         if (grow) {
;           alpha = __builtin_amdgcn_exp2f(-delta);
; #pragma unroll
;           for (int kt = 0; kt < 4; ++kt) s[qt][kt] -= delta;
.LBB0_1571:
	s_or_b64 exec, exec, s[18:19]
	v_max3_f32 v147, v128, s41, v129
	v_max3_f32 v147, v147, v130, v131
	v_max3_f32 v147, v147, v132, v133
	v_max3_f32 v147, v147, v134, v135
	v_max3_f32 v147, v147, v136, v137
	v_max3_f32 v147, v147, v138, v139
	v_max3_f32 v147, v147, v140, v141
	v_max3_f32 v147, v147, v142, v143
	v_mov_b32_e32 v157, v147
	s_nop 1
	v_permlane16_swap_b32_e32 v147, v157
	v_max_f32_e32 v147, v147, v157
	v_mov_b32_e32 v157, v147
	s_nop 1
	v_permlane32_swap_b32_e32 v147, v157
	v_max_f32_e32 v209, v147, v157
	v_max_f32_e32 v210, 0, v209
	v_cndmask_b32_e64 v147, v210, v209, s[4:5]
	v_cmp_neq_f32_e32 vcc, 0, v147
	s_cmp_lg_u64 vcc, 0
	s_cselect_b64 s[18:19], -1, 0
	s_cbranch_vccz .LBB0_1578
	v_exp_f32_e64 v168, -v147
	v_sub_f32_e32 v128, v128, v147
	v_sub_f32_e32 v129, v129, v147
	v_sub_f32_e32 v130, v130, v147
	v_sub_f32_e32 v131, v131, v147
	v_sub_f32_e32 v132, v132, v147
	v_sub_f32_e32 v133, v133, v147
	v_sub_f32_e32 v134, v134, v147
	v_sub_f32_e32 v135, v135, v147
	v_sub_f32_e32 v136, v136, v147
	v_sub_f32_e32 v137, v137, v147
	v_sub_f32_e32 v138, v138, v147
	v_sub_f32_e32 v139, v139, v147
	v_sub_f32_e32 v140, v140, v147
	v_sub_f32_e32 v141, v141, v147
	v_sub_f32_e32 v142, v142, v147
	v_sub_f32_e32 v143, v143, v147
	s_branch .LBB0_1579

; template <int MODE>
; DI void attn_item(const Params& p, int item, char* smem, u16* gdst) {
;     ...
;         float mx = -1e30f;
; #pragma unroll
;         for (int kt = 0; kt < 4; ++kt)
; #pragma unroll
;           for (int j = 0; j < 4; ++j) mx = fmaxf(mx, s[qt][kt][j]);
;         mx = xq_max(mx);
;         const float delta = (jt == 0) ? mx : fmaxf(mx, 0.f);
;         mrow[qt] = (jt == 0) ? delta : mrow[qt] + delta;
;         const bool grow = __ballot(delta != 0.f) != 0ull;
;         float alpha = 1.f;
;         if (grow) {
;           alpha = __builtin_amdgcn_exp2f(-delta);
; #pragma unroll
;           for (int kt = 0; kt < 4; ++kt) s[qt][kt] -= delta;
;         }
;         float rs = 0.f;
; #pragma unroll
;         for (int kt = 0; kt < 4; ++kt)
; #pragma unroll
;           for (int j = 0; j < 4; ++j) {
;             float pv = __builtin_amdgcn_exp2f(s[qt][kt][j]);
;             if (MODE == 1) {
;               int keep;
;               asm("v_bfe_i32 %0, %1, %2, 1" : "=v"(keep) : "v"(kt < 2 ? mlo[qt] : mhi[qt]), "n"((kt & 1) * 16 + j));
;               pv = __int_as_float(__float_as_int(pv) & keep);
;             }
;             s[qt][kt][j] = pv; rs += pv;
;           }
;         rs = xq_sum(rs);
;         lrow[qt] = lrow[qt] * alpha + rs;
;         if (grow) {
; #pragma unroll
;           for (int dt = 0; dt < 8; ++dt) o[qt][dt] *= alpha;
.LBB0_1579:
	v_exp_f32_e32 v128, v128
	v_exp_f32_e32 v129, v129
	v_exp_f32_e32 v130, v130
	v_exp_f32_e32 v131, v131
	v_lshrrev_b64 v[166:167], v156, v[166:167]
	v_bfe_i32 v147, v166, 0, 1
	v_exp_f32_e32 v132, v132
	v_and_b32_e32 v128, v147, v128
	v_bfe_i32 v157, v166, 1, 1
	v_and_b32_e32 v129, v157, v129
	v_exp_f32_e32 v133, v133
	v_add_f32_e32 v147, v128, v129
	v_bfe_i32 v157, v166, 2, 1
	v_exp_f32_e32 v134, v134
	v_and_b32_e32 v130, v157, v130
	v_bfe_i32 v169, v166, 3, 1
	v_add_f32_e32 v147, v147, v130
	v_and_b32_e32 v131, v169, v131
	v_exp_f32_e32 v135, v135
	v_add_f32_e32 v147, v147, v131
	v_bfe_i32 v157, v166, 16, 1
	v_exp_f32_e32 v136, v136
	v_and_b32_e32 v132, v157, v132
	v_bfe_i32 v169, v166, 17, 1
	v_add_f32_e32 v147, v147, v132
	v_and_b32_e32 v133, v169, v133
	v_exp_f32_e32 v137, v137
	v_add_f32_e32 v147, v147, v133
	v_bfe_i32 v157, v166, 18, 1
	v_exp_f32_e32 v138, v138
	v_and_b32_e32 v134, v157, v134
	v_bfe_i32 v166, v166, 19, 1
	v_add_f32_e32 v147, v147, v134
	v_and_b32_e32 v135, v166, v135
	v_exp_f32_e32 v139, v139
	v_add_f32_e32 v147, v147, v135
	v_bfe_i32 v157, v167, 0, 1
	v_exp_f32_e32 v140, v140
	v_and_b32_e32 v136, v157, v136
	v_bfe_i32 v166, v167, 1, 1
	v_add_f32_e32 v147, v147, v136
	v_and_b32_e32 v137, v166, v137
	v_exp_f32_e32 v141, v141
	v_add_f32_e32 v147, v147, v137
	v_bfe_i32 v157, v167, 2, 1
	v_exp_f32_e32 v142, v142
	v_and_b32_e32 v138, v157, v138
	v_bfe_i32 v166, v167, 3, 1
	v_add_f32_e32 v147, v147, v138
	v_and_b32_e32 v139, v166, v139
	v_exp_f32_e32 v143, v143
	v_add_f32_e32 v147, v147, v139
	v_bfe_i32 v157, v167, 16, 1
	v_bfe_i32 v166, v167, 17, 1
	s_andn2_b64 vcc, exec, s[18:19]
	v_and_b32_e32 v140, v157, v140
	v_and_b32_e32 v141, v166, v141
	v_add_f32_e32 v147, v147, v140
	v_add_f32_e32 v147, v147, v141
	v_bfe_i32 v157, v167, 18, 1
	v_bfe_i32 v166, v167, 19, 1
	s_nop 0
	v_and_b32_e32 v142, v157, v142
	v_and_b32_e32 v143, v166, v143
	v_add_f32_e32 v147, v147, v142
	v_add_f32_e32 v147, v147, v143
	v_mov_b32_e32 v157, v147
	s_nop 1
	v_permlane16_swap_b32_e32 v147, v157
	v_add_f32_e32 v211, v147, v157
	v_mov_b32_e32 v212, v211
	s_nop 1
	v_permlane32_swap_b32_e32 v211, v212
	s_cbranch_vccnz .LBB0_1581
	v_pk_mul_f32 v[94:95], v[94:95], v[168:169] op_sel_hi:[1,0]
	v_pk_mul_f32 v[92:93], v[92:93], v[168:169] op_sel_hi:[1,0]
	v_pk_mul_f32 v[90:91], v[90:91], v[168:169] op_sel_hi:[1,0]
	v_pk_mul_f32 v[88:89], v[88:89], v[168:169] op_sel_hi:[1,0]
	v_pk_mul_f32 v[86:87], v[86:87], v[168:169] op_sel_hi:[1,0]
	v_pk_mul_f32 v[84:85], v[84:85], v[168:169] op_sel_hi:[1,0]
	v_pk_mul_f32 v[82:83], v[82:83], v[168:169] op_sel_hi:[1,0]
	v_pk_mul_f32 v[80:81], v[80:81], v[168:169] op_sel_hi:[1,0]
	v_pk_mul_f32 v[50:51], v[50:51], v[168:169] op_sel_hi:[1,0]
	v_pk_mul_f32 v[48:49], v[48:49], v[168:169] op_sel_hi:[1,0]
	v_pk_mul_f32 v[42:43], v[42:43], v[168:169] op_sel_hi:[1,0]
	v_pk_mul_f32 v[40:41], v[40:41], v[168:169] op_sel_hi:[1,0]
	v_pk_mul_f32 v[38:39], v[38:39], v[168:169] op_sel_hi:[1,0]
	v_pk_mul_f32 v[36:37], v[36:37], v[168:169] op_sel_hi:[1,0]
	v_pk_mul_f32 v[34:35], v[34:35], v[168:169] op_sel_hi:[1,0]
	v_pk_mul_f32 v[32:33], v[32:33], v[168:169] op_sel_hi:[1,0]
.LBB0_1581:
	v_max3_f32 v147, v112, s41, v113
	v_max3_f32 v147, v147, v114, v115
	v_max3_f32 v147, v147, v116, v117
	v_max3_f32 v147, v147, v118, v119
	v_max3_f32 v147, v147, v120, v121
	v_max3_f32 v147, v147, v122, v123
	v_max3_f32 v147, v147, v124, v125
	v_max3_f32 v147, v147, v126, v127
	v_mov_b32_e32 v157, v147
	s_nop 1
	v_permlane16_swap_b32_e32 v147, v157
	v_max_f32_e32 v147, v147, v157
	v_mov_b32_e32 v157, v147
	s_nop 1
	v_permlane32_swap_b32_e32 v147, v157
	v_max_f32_e32 v213, v147, v157
	v_max_f32_e32 v214, 0, v213
	v_cndmask_b32_e64 v147, v214, v213, s[4:5]
	v_cmp_neq_f32_e32 vcc, 0, v147
	s_cmp_lg_u64 vcc, 0
	s_cselect_b64 s[18:19], -1, 0
	s_cbranch_vccz .LBB0_1583
	v_exp_f32_e64 v166, -v147
	v_sub_f32_e32 v112, v112, v147
	v_sub_f32_e32 v113, v113, v147
	v_sub_f32_e32 v114, v114, v147
	v_sub_f32_e32 v115, v115, v147
	v_sub_f32_e32 v116, v116, v147
	v_sub_f32_e32 v117, v117, v147
	v_sub_f32_e32 v118, v118, v147
	v_sub_f32_e32 v119, v119, v147
	v_sub_f32_e32 v120, v120, v147
	v_sub_f32_e32 v121, v121, v147
	v_sub_f32_e32 v122, v122, v147
	v_sub_f32_e32 v123, v123, v147
	v_sub_f32_e32 v124, v124, v147
	v_sub_f32_e32 v125, v125, v147
	v_sub_f32_e32 v126, v126, v147
	v_sub_f32_e32 v127, v127, v147
	s_branch .LBB0_1584

; template <int MODE>
; DI void attn_item(const Params& p, int item, char* smem, u16* gdst) {
;     ...
;         float rs = 0.f;
; #pragma unroll
;         for (int kt = 0; kt < 4; ++kt)
; #pragma unroll
;           for (int j = 0; j < 4; ++j) {
;             float pv = __builtin_amdgcn_exp2f(s[qt][kt][j]);
;             if (MODE == 1) {
;               int keep;
;               asm("v_bfe_i32 %0, %1, %2, 1" : "=v"(keep) : "v"(kt < 2 ? mlo[qt] : mhi[qt]), "n"((kt & 1) * 16 + j));
;               pv = __int_as_float(__float_as_int(pv) & keep);
;             }
;             s[qt][kt][j] = pv; rs += pv;
;           }
;         rs = xq_sum(rs);
;         lrow[qt] = lrow[qt] * alpha + rs;
;         if (grow) {
; #pragma unroll
;           for (int dt = 0; dt < 8; ++dt) o[qt][dt] *= alpha;
.LBB0_1584:
	v_exp_f32_e32 v113, v113
	v_lshrrev_b64 v[216:217], v156, v[164:165]
	v_exp_f32_e32 v112, v112
	v_bfe_i32 v147, v216, 1, 1
	v_exp_f32_e32 v114, v114
	v_and_b32_e32 v147, v147, v113
	v_exp_f32_e32 v113, v115
	v_bfe_i32 v157, v216, 0, 1
	v_bfe_i32 v115, v216, 2, 1
	s_andn2_b64 vcc, exec, s[18:19]
	v_and_b32_e32 v164, v157, v112
	v_bfe_i32 v157, v216, 3, 1
	v_and_b32_e32 v170, v115, v114
	v_and_b32_e32 v157, v157, v113
	v_exp_f32_e32 v113, v117
	v_exp_f32_e32 v114, v116
	v_bfe_i32 v116, v216, 17, 1
	v_bfe_i32 v115, v216, 16, 1
	v_and_b32_e32 v117, v116, v113
	v_and_b32_e32 v116, v115, v114
	v_exp_f32_e32 v113, v119
	v_exp_f32_e32 v114, v118
	v_bfe_i32 v118, v216, 19, 1
	v_bfe_i32 v115, v216, 18, 1
	v_add_f32_e32 v112, v164, v147
	v_and_b32_e32 v119, v118, v113
	v_and_b32_e32 v118, v115, v114
	v_exp_f32_e32 v114, v120
	v_exp_f32_e32 v113, v121
	v_bfe_i32 v115, v217, 0, 1
	v_add_f32_e32 v112, v112, v170
	v_and_b32_e32 v172, v115, v114
	v_exp_f32_e32 v114, v122
	v_bfe_i32 v120, v217, 1, 1
	v_add_f32_e32 v112, v112, v157
	v_and_b32_e32 v165, v120, v113
	v_exp_f32_e32 v113, v123
	v_add_f32_e32 v112, v112, v116
	v_add_f32_e32 v112, v112, v117
	v_bfe_i32 v115, v217, 2, 1
	v_add_f32_e32 v112, v112, v118
	v_and_b32_e32 v174, v115, v114
	v_exp_f32_e32 v114, v124
	v_bfe_i32 v120, v217, 3, 1
	v_add_f32_e32 v112, v112, v119
	v_and_b32_e32 v167, v120, v113
	v_exp_f32_e32 v113, v125
	v_add_f32_e32 v112, v112, v172
	v_add_f32_e32 v112, v112, v165
	v_bfe_i32 v115, v217, 16, 1
	v_add_f32_e32 v112, v112, v174
	v_and_b32_e32 v176, v115, v114
	v_exp_f32_e32 v114, v126
	v_bfe_i32 v120, v217, 17, 1
	v_add_f32_e32 v112, v112, v167
	v_and_b32_e32 v169, v120, v113
	v_exp_f32_e32 v113, v127
	v_add_f32_e32 v112, v112, v176
	v_add_f32_e32 v112, v112, v169
	v_bfe_i32 v115, v217, 18, 1
	v_bfe_i32 v120, v217, 19, 1
	s_nop 0
	v_and_b32_e32 v178, v115, v114
	v_and_b32_e32 v171, v120, v113
	v_add_f32_e32 v112, v112, v178
	v_add_f32_e32 v112, v112, v171
	v_mov_b32_e32 v113, v112
	s_nop 1
	v_permlane16_swap_b32_e32 v112, v113
	v_add_f32_e32 v112, v112, v113
	v_mov_b32_e32 v113, v112
	s_nop 1
	v_permlane32_swap_b32_e32 v112, v113
	s_cbranch_vccnz .LBB0_1586
	v_pk_mul_f32 v[30:31], v[30:31], v[166:167] op_sel_hi:[1,0]
	v_pk_mul_f32 v[28:29], v[28:29], v[166:167] op_sel_hi:[1,0]
	v_pk_mul_f32 v[26:27], v[26:27], v[166:167] op_sel_hi:[1,0]
	v_pk_mul_f32 v[24:25], v[24:25], v[166:167] op_sel_hi:[1,0]
	v_pk_mul_f32 v[22:23], v[22:23], v[166:167] op_sel_hi:[1,0]
	v_pk_mul_f32 v[20:21], v[20:21], v[166:167] op_sel_hi:[1,0]
	v_pk_mul_f32 v[18:19], v[18:19], v[166:167] op_sel_hi:[1,0]
	v_pk_mul_f32 v[16:17], v[16:17], v[166:167] op_sel_hi:[1,0]
	v_pk_mul_f32 v[14:15], v[14:15], v[166:167] op_sel_hi:[1,0]
	v_pk_mul_f32 v[12:13], v[12:13], v[166:167] op_sel_hi:[1,0]
	v_pk_mul_f32 v[10:11], v[10:11], v[166:167] op_sel_hi:[1,0]
	v_pk_mul_f32 v[8:9], v[8:9], v[166:167] op_sel_hi:[1,0]
	v_pk_mul_f32 v[6:7], v[6:7], v[166:167] op_sel_hi:[1,0]
	v_pk_mul_f32 v[4:5], v[4:5], v[166:167] op_sel_hi:[1,0]
	v_pk_mul_f32 v[2:3], v[2:3], v[166:167] op_sel_hi:[1,0]
	v_pk_mul_f32 v[0:1], v[0:1], v[166:167] op_sel_hi:[1,0]

; template <int MODE>
; DI void attn_item(const Params& p, int item, char* smem, u16* gdst) {
;     ...
;     __syncthreads();
;     if (!direct) {
;       if (jt + 1 < ntiles) KV_STORE((jt + 1) & 1)
;       KV_LOAD(min(jt + 2, ntiles - 1))
;     ...
;       for (int kt = 0; kt < 4; ++kt) {
; #pragma unroll
;         for (int ks = 0; ks < NKS; ++ks) {
;           bf16x8 kf = *(const bf16x8*)(sK + (kt * 16 + fr) * KSTR + (ks >> 1) * 64 + ((ks & 1) ? ko1 : ko0));
;           s[0][kt] = __builtin_amdgcn_mfma_f32_16x16x32_bf16(kf, qf[0][ks], s[0][kt], 0, 0, 0);
;           s[1][kt] = __builtin_amdgcn_mfma_f32_16x16x32_bf16(kf, qf[1][ks], s[1][kt], 0, 0, 0);
;         }
;       }
.LBB0_1798:
	s_add_i32 s17, s0, 1
	s_waitcnt lgkmcnt(0)
	s_barrier
	s_bitcmp1_b32 s0, 0
	s_cselect_b32 s36, 0xa800, 0
	v_add_u32_e32 v211, s36, v200
	v_add_u32_e32 v210, v211, v199
	v_add_u32_e32 v211, v211, v191
	ds_read_b128 v[232:235], v210
	ds_read_b128 v[236:239], v211
	ds_read_b128 v[240:243], v210 offset:128
	ds_read_b128 v[244:247], v211 offset:128
	ds_read_b128 v[248:251], v210 offset:256
	s_cmp_ge_i32 s17, s34
	s_cbranch_scc1 .LBB0_1800
	s_bitcmp1_b32 s17, 0
	s_cselect_b32 s1, 0xa800, 0
	s_add_i32 s1, s1, 0
	v_add3_u32 v0, s1, v189, v173
	s_waitcnt vmcnt(4)
	ds_write_b128 v0, v[52:55]
	s_waitcnt vmcnt(3)
	ds_write_b128 v0, v[56:59] offset:12288
	v_lshl_add_u32 v0, v187, 1, s1
	v_lshl_add_u32 v52, v190, 1, v0
	v_add3_u32 v0, v0, v188, v172
	s_waitcnt vmcnt(2)
	ds_write_b128 v52, v[60:63] offset:256
	s_waitcnt vmcnt(1)
	ds_write_b128 v0, v[64:67] offset:24576
	s_waitcnt vmcnt(0)
	ds_write_b128 v0, v[68:71] offset:33792
.LBB0_1800:
	s_add_i32 s1, s0, 2
	s_min_i32 s1, s1, s13
	s_lshl_b32 s4, s1, 6
	s_add_i32 s6, s4, s12
	s_ashr_i32 s7, s6, 31
	s_waitcnt vmcnt(4)
	v_lshl_add_u64 v[52:53], s[6:7], 0, v[168:169]
	v_lshlrev_b64 v[52:53], 12, v[52:53]
	v_lshl_add_u64 v[52:53], v[2:3], 0, v[52:53]
	s_waitcnt vmcnt(2)
	v_lshl_add_u64 v[60:61], s[6:7], 0, v[170:171]
	s_ashr_i32 s5, s4, 31
	v_add_co_u32_e32 v56, vcc, 0x20000, v52
	v_lshlrev_b64 v[60:61], 7, v[60:61]
	s_waitcnt vmcnt(1)
	v_lshl_add_u64 v[64:65], s[4:5], 1, v[174:175]
	v_addc_co_u32_e32 v57, vcc, 0, v53, vcc
	v_lshl_add_u64 v[60:61], v[176:177], 0, v[60:61]
	s_waitcnt vmcnt(0)
	v_lshl_add_u64 v[68:69], v[64:65], 0, s[10:11]
	global_load_dwordx4 v[52:55], v[52:53], off
	s_nop 0
	global_load_dwordx4 v[56:59], v[56:57], off
	v_cmp_lt_i32_e32 vcc, s0, v185
	global_load_dwordx4 v[60:63], v[60:61], off
	s_nop 0
	global_load_dwordx4 v[64:67], v[64:65], off
	s_nop 0
	global_load_dwordx4 v[68:71], v[68:69], off
	s_and_b64 s[4:5], s[2:3], vcc
	s_and_saveexec_b64 s[14:15], s[4:5]
	s_cbranch_execz .LBB0_1814
	v_xor_b32_e32 v148, 0x80000000, v201
	v_xor_b32_e32 v164, 0x80000000, v203
	v_mov_b32_e32 v149, v148
	v_mov_b32_e32 v150, v148
	v_mov_b32_e32 v151, v148
	v_mov_b32_e32 v165, v164
	v_mov_b32_e32 v166, v164
	v_mov_b32_e32 v167, v164
	s_waitcnt lgkmcnt(4)
	v_mfma_f32_16x16x32_bf16 v[152:155], v[232:235], v[4:7], v[148:151]
	v_mfma_f32_16x16x32_bf16 v[136:139], v[232:235], v[28:31], v[164:167]
	ds_read_b128 v[232:235], v211 offset:256
	s_waitcnt lgkmcnt(4)
	v_mfma_f32_16x16x32_bf16 v[152:155], v[236:239], v[8:11], v[152:155]
	v_mfma_f32_16x16x32_bf16 v[136:139], v[236:239], v[32:35], v[136:139]
	v_add_u32_e32 v211, s36, v205
	v_add_u32_e32 v210, v211, v199
	v_add_u32_e32 v211, v211, v191
	ds_read_b128 v[236:239], v210
	s_waitcnt lgkmcnt(4)
	v_mfma_f32_16x16x32_bf16 v[152:155], v[240:243], v[12:15], v[152:155]
	v_mfma_f32_16x16x32_bf16 v[136:139], v[240:243], v[36:39], v[136:139]
	ds_read_b128 v[240:243], v211
	s_waitcnt lgkmcnt(4)
	v_mfma_f32_16x16x32_bf16 v[152:155], v[244:247], v[16:19], v[152:155]
	v_mfma_f32_16x16x32_bf16 v[136:139], v[244:247], v[40:43], v[136:139]
	ds_read_b128 v[244:247], v210 offset:128
	s_waitcnt lgkmcnt(4)
	v_mfma_f32_16x16x32_bf16 v[152:155], v[248:251], v[20:23], v[152:155]
	v_mfma_f32_16x16x32_bf16 v[136:139], v[248:251], v[44:47], v[136:139]
	ds_read_b128 v[248:251], v211 offset:128
	s_waitcnt lgkmcnt(4)
	v_mfma_f32_16x16x32_bf16 v[152:155], v[232:235], v[24:27], v[152:155]
	v_mfma_f32_16x16x32_bf16 v[136:139], v[232:235], v[48:51], v[136:139]
	ds_read_b128 v[232:235], v210 offset:256
	s_waitcnt lgkmcnt(4)
	v_mfma_f32_16x16x32_bf16 v[156:159], v[236:239], v[4:7], v[148:151]
	v_mfma_f32_16x16x32_bf16 v[140:143], v[236:239], v[28:31], v[164:167]
	ds_read_b128 v[236:239], v211 offset:256
	s_waitcnt lgkmcnt(4)
	v_mfma_f32_16x16x32_bf16 v[156:159], v[240:243], v[8:11], v[156:159]
	v_mfma_f32_16x16x32_bf16 v[140:143], v[240:243], v[32:35], v[140:143]
	v_add_u32_e32 v211, s36, v206
	v_add_u32_e32 v210, v211, v199
	v_add_u32_e32 v211, v211, v191
	ds_read_b128 v[240:243], v210
	s_waitcnt lgkmcnt(4)
	v_mfma_f32_16x16x32_bf16 v[156:159], v[244:247], v[12:15], v[156:159]
	v_mfma_f32_16x16x32_bf16 v[140:143], v[244:247], v[36:39], v[140:143]
	ds_read_b128 v[244:247], v211
	s_waitcnt lgkmcnt(4)
	v_mfma_f32_16x16x32_bf16 v[156:159], v[248:251], v[16:19], v[156:159]
	v_mfma_f32_16x16x32_bf16 v[140:143], v[248:251], v[40:43], v[140:143]
	ds_read_b128 v[248:251], v210 offset:128
	s_waitcnt lgkmcnt(4)
	v_mfma_f32_16x16x32_bf16 v[156:159], v[232:235], v[20:23], v[156:159]
	v_mfma_f32_16x16x32_bf16 v[140:143], v[232:235], v[44:47], v[140:143]
	ds_read_b128 v[232:235], v211 offset:128
	s_waitcnt lgkmcnt(4)
	v_mfma_f32_16x16x32_bf16 v[156:159], v[236:239], v[24:27], v[156:159]
	v_mfma_f32_16x16x32_bf16 v[140:143], v[236:239], v[48:51], v[140:143]
	ds_read_b128 v[236:239], v210 offset:256
	s_waitcnt lgkmcnt(4)
	v_mfma_f32_16x16x32_bf16 v[160:163], v[240:243], v[4:7], v[148:151]
	v_mfma_f32_16x16x32_bf16 v[144:147], v[240:243], v[28:31], v[164:167]
	ds_read_b128 v[240:243], v211 offset:256
	s_waitcnt lgkmcnt(4)
	v_mfma_f32_16x16x32_bf16 v[160:163], v[244:247], v[8:11], v[160:163]
	v_mfma_f32_16x16x32_bf16 v[144:147], v[244:247], v[32:35], v[144:147]
	v_add_u32_e32 v211, s36, v207
	v_add_u32_e32 v210, v211, v199
	v_add_u32_e32 v211, v211, v191
	ds_read_b128 v[244:247], v210
	s_waitcnt lgkmcnt(4)
	v_mfma_f32_16x16x32_bf16 v[160:163], v[248:251], v[12:15], v[160:163]
	v_mfma_f32_16x16x32_bf16 v[144:147], v[248:251], v[36:39], v[144:147]
	ds_read_b128 v[248:251], v211
	s_waitcnt lgkmcnt(4)
; template <int MODE>
; DI void attn_item(const Params& p, int item, char* smem, u16* gdst) {
;     ...
;       for (int kt = 0; kt < 4; ++kt) {
; #pragma unroll
;         for (int ks = 0; ks < NKS; ++ks) {
;           bf16x8 kf = *(const bf16x8*)(sK + (kt * 16 + fr) * KSTR + (ks >> 1) * 64 + ((ks & 1) ? ko1 : ko0));
;           s[0][kt] = __builtin_amdgcn_mfma_f32_16x16x32_bf16(kf, qf[0][ks], s[0][kt], 0, 0, 0);
;           s[1][kt] = __builtin_amdgcn_mfma_f32_16x16x32_bf16(kf, qf[1][ks], s[1][kt], 0, 0, 0);
;         }
;       }
;       unsigned mlo[2] = {0u, 0u}, mhi[2] = {0u, 0u};
;       if (MODE == 0) {
;         if (key0 + 64 > nkeys) {
; #pragma unroll
;           for (int kt = 0; kt < 4; ++kt)
; #pragma unroll
;             for (int j = 0; j < 4; ++j)
;               if (key0 + kt * 16 + fq * 4 + j >= nkeys) { s[0][kt][j] = -1e30f; s[1][kt][j] = -1e30f; }
;         }
;       } else {
;         const bool far = (key0 + 63) - (qpos0 + wq0) <= -128;
;         if (!far) {
; #pragma unroll
;           for (int qt = 0; qt < 2; ++qt) {
;             const int rb = key0 + fq * 4 - (qpos0 + qrow[qt]) + 128;
; #pragma unroll
;             for (int kt = 0; kt < 4; ++kt)
; #pragma unroll
;               for (int j = 0; j < 4; ++j) {
;                 int r = min(max(rb + kt * 16 + j, 0), 256);
;                 s[qt][kt][j] += sBias[r];
;               }
;           }
;         }
; #pragma unroll
;         for (int qt = 0; qt < 2; ++qt) {
;           const unsigned long long mm = mq[qt] >> (fq * 4);
;           mlo[qt] = (unsigned)mm; mhi[qt] = (unsigned)(mm >> 32);
;         }
;       }
;       bf16x8 pf[2][2];
; #pragma unroll
;       for (int qt = 0; qt < 2; ++qt) {
;         float mx = -1e30f;
; #pragma unroll
;         for (int kt = 0; kt < 4; ++kt)
; #pragma unroll
;           for (int j = 0; j < 4; ++j) mx = fmaxf(mx, s[qt][kt][j]);
;         mx = xq_max(mx);
;         const float delta = (jt == 0) ? mx : fmaxf(mx, 0.f);
;         mrow[qt] = (jt == 0) ? delta : mrow[qt] + delta;
;         const bool grow = __ballot(delta != 0.f) != 0ull;
;         float alpha = 1.f;
;         if (grow) {
;           alpha = __builtin_amdgcn_exp2f(-delta);
; #pragma unroll
;           for (int kt = 0; kt < 4; ++kt) s[qt][kt] -= delta;
	v_mfma_f32_16x16x32_bf16 v[160:163], v[232:235], v[16:19], v[160:163]
	v_mfma_f32_16x16x32_bf16 v[144:147], v[232:235], v[40:43], v[144:147]
	ds_read_b128 v[232:235], v210 offset:128
	s_waitcnt lgkmcnt(4)
	v_mfma_f32_16x16x32_bf16 v[160:163], v[236:239], v[20:23], v[160:163]
	v_mfma_f32_16x16x32_bf16 v[144:147], v[236:239], v[44:47], v[144:147]
	ds_read_b128 v[236:239], v211 offset:128
	s_waitcnt lgkmcnt(4)
	v_mfma_f32_16x16x32_bf16 v[160:163], v[240:243], v[24:27], v[160:163]
	v_mfma_f32_16x16x32_bf16 v[144:147], v[240:243], v[48:51], v[144:147]
	ds_read_b128 v[240:243], v210 offset:256
	s_waitcnt lgkmcnt(4)
	v_mfma_f32_16x16x32_bf16 v[252:255], v[244:247], v[4:7], v[148:151]
	v_mfma_f32_16x16x32_bf16 v[148:151], v[244:247], v[28:31], v[164:167]
	ds_read_b128 v[244:247], v211 offset:256
	s_waitcnt lgkmcnt(4)
	v_mfma_f32_16x16x32_bf16 v[252:255], v[248:251], v[8:11], v[252:255]
	v_mfma_f32_16x16x32_bf16 v[148:151], v[248:251], v[32:35], v[148:151]
	s_waitcnt lgkmcnt(3)
	v_mfma_f32_16x16x32_bf16 v[252:255], v[232:235], v[12:15], v[252:255]
	v_mfma_f32_16x16x32_bf16 v[148:151], v[232:235], v[36:39], v[148:151]
	s_waitcnt lgkmcnt(2)
	v_mfma_f32_16x16x32_bf16 v[252:255], v[236:239], v[16:19], v[252:255]
	v_mfma_f32_16x16x32_bf16 v[148:151], v[236:239], v[40:43], v[148:151]
	s_waitcnt lgkmcnt(1)
	v_mfma_f32_16x16x32_bf16 v[252:255], v[240:243], v[20:23], v[252:255]
	v_mfma_f32_16x16x32_bf16 v[148:151], v[240:243], v[44:47], v[148:151]
	s_waitcnt lgkmcnt(0)
	v_mfma_f32_16x16x32_bf16 v[164:167], v[244:247], v[24:27], v[252:255]
	v_mfma_f32_16x16x32_bf16 v[148:151], v[244:247], v[48:51], v[148:151]
	s_cmp_le_i32 s16, s33
	s_cbranch_scc1 .LBB0_1803
	v_add_u32_e32 v0, s16, v208
	v_subrev_u32_e32 v209, 64, v0
	v_cmp_gt_i32_e32 vcc, s33, v209
	v_subrev_u32_e32 v209, 63, v0
	v_cmp_gt_i32_e64 s[4:5], s33, v209
	v_subrev_u32_e32 v209, 62, v0
	v_cmp_gt_i32_e64 s[6:7], s33, v209
	v_subrev_u32_e32 v209, 61, v0
	v_cmp_gt_i32_e64 s[8:9], s33, v209
	s_or_b64 s[6:7], s[8:9], s[6:7]
	s_or_b64 s[4:5], s[6:7], s[4:5]
	s_or_b64 vcc, s[4:5], vcc
	v_subrev_u32_e32 v209, 48, v0
	v_cndmask_b32_e32 v136, v183, v136, vcc
	v_cndmask_b32_e32 v152, v183, v152, vcc
	v_cmp_gt_i32_e32 vcc, s33, v209
	v_subrev_u32_e32 v209, 47, v0
	v_cndmask_b32_e64 v137, v183, v137, s[4:5]
	v_cndmask_b32_e64 v153, v183, v153, s[4:5]
	v_cmp_gt_i32_e64 s[4:5], s33, v209
	v_subrev_u32_e32 v209, 46, v0
	v_cndmask_b32_e64 v138, v183, v138, s[6:7]
	v_cndmask_b32_e64 v154, v183, v154, s[6:7]
	v_cmp_gt_i32_e64 s[6:7], s33, v209
	v_subrev_u32_e32 v209, 45, v0
	v_cndmask_b32_e64 v139, v183, v139, s[8:9]
	v_cndmask_b32_e64 v155, v183, v155, s[8:9]
	v_cmp_gt_i32_e64 s[8:9], s33, v209
	s_or_b64 s[6:7], s[8:9], s[6:7]
	s_or_b64 s[4:5], s[6:7], s[4:5]
	s_or_b64 vcc, s[4:5], vcc
	v_subrev_u32_e32 v209, 32, v0
	v_cndmask_b32_e32 v140, v183, v140, vcc
	v_cndmask_b32_e32 v156, v183, v156, vcc
	v_cmp_gt_i32_e32 vcc, s33, v209
	v_subrev_u32_e32 v209, 31, v0
	v_cndmask_b32_e64 v141, v183, v141, s[4:5]
	v_cndmask_b32_e64 v157, v183, v157, s[4:5]
	v_cmp_gt_i32_e64 s[4:5], s33, v209
	v_subrev_u32_e32 v209, 30, v0
	v_cndmask_b32_e64 v142, v183, v142, s[6:7]
	v_cndmask_b32_e64 v158, v183, v158, s[6:7]
	v_cmp_gt_i32_e64 s[6:7], s33, v209
	v_subrev_u32_e32 v209, 29, v0
	v_cndmask_b32_e64 v143, v183, v143, s[8:9]
	v_cndmask_b32_e64 v159, v183, v159, s[8:9]
	v_cmp_gt_i32_e64 s[8:9], s33, v209
	s_or_b64 s[6:7], s[8:9], s[6:7]
	s_or_b64 s[4:5], s[6:7], s[4:5]
	s_or_b64 vcc, s[4:5], vcc
	v_add_u32_e32 v209, -16, v0
	v_cndmask_b32_e32 v144, v183, v144, vcc
	v_cndmask_b32_e32 v160, v183, v160, vcc
	v_cmp_gt_i32_e32 vcc, s33, v209
	v_add_u32_e32 v209, -15, v0
	v_cndmask_b32_e64 v145, v183, v145, s[4:5]
	v_cndmask_b32_e64 v161, v183, v161, s[4:5]
	v_cmp_gt_i32_e64 s[4:5], s33, v209
	v_add_u32_e32 v209, -14, v0
	v_add_u32_e32 v0, -13, v0
	v_cndmask_b32_e64 v147, v183, v147, s[8:9]
	v_cndmask_b32_e64 v146, v183, v146, s[6:7]
	v_cndmask_b32_e64 v162, v183, v162, s[6:7]
	v_cndmask_b32_e64 v163, v183, v163, s[8:9]
	v_cmp_gt_i32_e64 s[6:7], s33, v209
	v_cmp_gt_i32_e64 s[8:9], s33, v0
	s_or_b64 s[6:7], s[8:9], s[6:7]
	s_or_b64 s[4:5], s[6:7], s[4:5]
	s_or_b64 vcc, s[4:5], vcc
	v_cndmask_b32_e64 v151, v183, v151, s[8:9]
	v_cndmask_b32_e64 v150, v183, v150, s[6:7]
	v_cndmask_b32_e64 v149, v183, v149, s[4:5]
	v_cndmask_b32_e32 v148, v183, v148, vcc
	v_cndmask_b32_e64 v166, v183, v166, s[6:7]
	v_cndmask_b32_e64 v165, v183, v165, s[4:5]
	v_cndmask_b32_e32 v164, v183, v164, vcc
	v_cndmask_b32_e64 v167, v183, v167, s[8:9]
.LBB0_1803:
	v_max3_f32 v0, v152, s26, v153
	v_max3_f32 v0, v0, v154, v155
	v_max3_f32 v0, v0, v156, v157
	v_max3_f32 v0, v0, v158, v159
	v_max3_f32 v0, v0, v160, v161
	v_max3_f32 v0, v0, v162, v163
	v_max3_f32 v0, v0, v164, v165
	v_max3_f32 v0, v0, v166, v167
	v_mov_b32_e32 v209, v0
	s_nop 1
	v_permlane16_swap_b32_e32 v0, v209
	v_max_f32_e32 v0, v0, v209
	v_mov_b32_e32 v209, v0
	s_nop 1
	v_permlane32_swap_b32_e32 v0, v209
	v_max3_f32 v209, v0, v209, 0
	v_cmp_neq_f32_e32 vcc, 0, v209
	s_cmp_lg_u64 vcc, 0
	s_cselect_b64 s[0:1], -1, 0
	s_cbranch_vccz .LBB0_1805
	v_exp_f32_e64 v0, -v209
	v_sub_f32_e32 v152, v152, v209
	v_sub_f32_e32 v153, v153, v209
	v_sub_f32_e32 v154, v154, v209
	v_sub_f32_e32 v155, v155, v209
	v_sub_f32_e32 v156, v156, v209
	v_sub_f32_e32 v157, v157, v209
	v_sub_f32_e32 v158, v158, v209
	v_sub_f32_e32 v159, v159, v209
	v_sub_f32_e32 v160, v160, v209
	v_sub_f32_e32 v161, v161, v209
	v_sub_f32_e32 v162, v162, v209
	v_sub_f32_e32 v163, v163, v209
	v_sub_f32_e32 v164, v164, v209
	v_sub_f32_e32 v165, v165, v209
	v_sub_f32_e32 v166, v166, v209
	v_sub_f32_e32 v167, v167, v209
	s_branch .LBB0_1806

; template <int MODE>
; DI void attn_item(const Params& p, int item, char* smem, u16* gdst) {
;     ...
;         float mx = -1e30f;
; #pragma unroll
;         for (int kt = 0; kt < 4; ++kt)
; #pragma unroll
;           for (int j = 0; j < 4; ++j) mx = fmaxf(mx, s[qt][kt][j]);
;         mx = xq_max(mx);
;         const float delta = (jt == 0) ? mx : fmaxf(mx, 0.f);
;         mrow[qt] = (jt == 0) ? delta : mrow[qt] + delta;
;         const bool grow = __ballot(delta != 0.f) != 0ull;
;         float alpha = 1.f;
;         if (grow) {
;           alpha = __builtin_amdgcn_exp2f(-delta);
; #pragma unroll
;           for (int kt = 0; kt < 4; ++kt) s[qt][kt] -= delta;
;         }
;         float rs = 0.f;
; #pragma unroll
;         for (int kt = 0; kt < 4; ++kt)
; #pragma unroll
;           for (int j = 0; j < 4; ++j) {
;             float pv = __builtin_amdgcn_exp2f(s[qt][kt][j]);
;             if (MODE == 1) {
;               int keep;
;               asm("v_bfe_i32 %0, %1, %2, 1" : "=v"(keep) : "v"(kt < 2 ? mlo[qt] : mhi[qt]), "n"((kt & 1) * 16 + j));
;               pv = __int_as_float(__float_as_int(pv) & keep);
;             }
;             s[qt][kt][j] = pv; rs += pv;
;           }
;         rs = xq_sum(rs);
;         lrow[qt] = lrow[qt] * alpha + rs;
;         if (grow) {
; #pragma unroll
;           for (int dt = 0; dt < 8; ++dt) o[qt][dt] *= alpha;
.LBB0_1806:
	v_exp_f32_e32 v210, v152
	v_exp_f32_e32 v211, v153
	v_exp_f32_e32 v212, v154
	v_exp_f32_e32 v155, v155
	v_exp_f32_e32 v156, v156
	v_add_f32_e32 v152, v210, v211
	v_exp_f32_e32 v157, v157
	v_add_f32_e32 v152, v212, v152
	v_exp_f32_e32 v213, v158
	v_add_f32_e32 v152, v155, v152
	v_exp_f32_e32 v214, v159
	v_add_f32_e32 v152, v156, v152
	v_exp_f32_e32 v215, v160
	v_add_f32_e32 v152, v157, v152
	v_exp_f32_e32 v216, v161
	v_add_f32_e32 v152, v213, v152
	v_exp_f32_e32 v162, v162
	v_add_f32_e32 v152, v214, v152
	v_exp_f32_e32 v163, v163
	v_add_f32_e32 v152, v215, v152
	v_exp_f32_e32 v158, v164
	v_add_f32_e32 v152, v216, v152
	v_exp_f32_e32 v159, v165
	v_add_f32_e32 v152, v162, v152
	v_exp_f32_e32 v160, v166
	v_add_f32_e32 v152, v163, v152
	v_exp_f32_e32 v161, v167
	v_add_f32_e32 v152, v158, v152
	v_add_f32_e32 v152, v159, v152
	v_add_f32_e32 v152, v160, v152
	v_add_f32_e32 v152, v161, v152
	v_mov_b32_e32 v153, v152
	s_nop 1
	v_permlane16_swap_b32_e32 v152, v153
	v_add_f32_e32 v153, v152, v153
	v_mov_b32_e32 v154, v153
	s_andn2_b64 vcc, exec, s[0:1]
	s_nop 0
	v_permlane32_swap_b32_e32 v153, v154
	s_cbranch_vccnz .LBB0_1808
	v_pk_mul_f32 v[126:127], v[126:127], v[0:1] op_sel_hi:[1,0]
	v_pk_mul_f32 v[124:125], v[124:125], v[0:1] op_sel_hi:[1,0]
	v_pk_mul_f32 v[130:131], v[130:131], v[0:1] op_sel_hi:[1,0]
	v_pk_mul_f32 v[128:129], v[128:129], v[0:1] op_sel_hi:[1,0]
	v_pk_mul_f32 v[134:135], v[134:135], v[0:1] op_sel_hi:[1,0]
	v_pk_mul_f32 v[132:133], v[132:133], v[0:1] op_sel_hi:[1,0]
	v_pk_mul_f32 v[122:123], v[122:123], v[0:1] op_sel_hi:[1,0]
	v_pk_mul_f32 v[120:121], v[120:121], v[0:1] op_sel_hi:[1,0]
	v_pk_mul_f32 v[106:107], v[106:107], v[0:1] op_sel_hi:[1,0]
	v_pk_mul_f32 v[104:105], v[104:105], v[0:1] op_sel_hi:[1,0]
	v_pk_mul_f32 v[110:111], v[110:111], v[0:1] op_sel_hi:[1,0]
	v_pk_mul_f32 v[108:109], v[108:109], v[0:1] op_sel_hi:[1,0]
	v_pk_mul_f32 v[114:115], v[114:115], v[0:1] op_sel_hi:[1,0]
	v_pk_mul_f32 v[112:113], v[112:113], v[0:1] op_sel_hi:[1,0]
	v_pk_mul_f32 v[118:119], v[118:119], v[0:1] op_sel_hi:[1,0]
	v_pk_mul_f32 v[116:117], v[116:117], v[0:1] op_sel_hi:[1,0]
.LBB0_1808:
	v_max3_f32 v152, v136, s26, v137
	v_max3_f32 v152, v152, v138, v139
	v_max3_f32 v152, v152, v140, v141
	v_max3_f32 v152, v152, v142, v143
	v_max3_f32 v152, v152, v144, v145
	v_max3_f32 v152, v152, v146, v147
	v_max3_f32 v152, v152, v148, v149
	v_max3_f32 v152, v152, v150, v151
	v_mov_b32_e32 v164, v152
	s_nop 1
	v_permlane16_swap_b32_e32 v152, v164
	v_max_f32_e32 v152, v152, v164
	v_mov_b32_e32 v164, v152
	s_nop 1
	v_permlane32_swap_b32_e32 v152, v164
	v_max3_f32 v164, v152, v164, 0
	v_cmp_neq_f32_e32 vcc, 0, v164
	s_cmp_lg_u64 vcc, 0
	s_cselect_b64 s[0:1], -1, 0
	s_cbranch_vccz .LBB0_1810
	v_exp_f32_e64 v152, -v164
	v_sub_f32_e32 v136, v136, v164
	v_sub_f32_e32 v137, v137, v164
	v_sub_f32_e32 v138, v138, v164
	v_sub_f32_e32 v139, v139, v164
	v_sub_f32_e32 v140, v140, v164
	v_sub_f32_e32 v141, v141, v164
	v_sub_f32_e32 v142, v142, v164
	v_sub_f32_e32 v143, v143, v164
	v_sub_f32_e32 v144, v144, v164
	v_sub_f32_e32 v145, v145, v164
	v_sub_f32_e32 v146, v146, v164
	v_sub_f32_e32 v147, v147, v164
	v_sub_f32_e32 v148, v148, v164
	v_sub_f32_e32 v149, v149, v164
	v_sub_f32_e32 v150, v150, v164
	v_sub_f32_e32 v151, v151, v164
	s_branch .LBB0_1811

; template <int MODE>
; DI void attn_item(const Params& p, int item, char* smem, u16* gdst) {
;     ...
;         float rs = 0.f;
; #pragma unroll
;         for (int kt = 0; kt < 4; ++kt)
; #pragma unroll
;           for (int j = 0; j < 4; ++j) {
;             float pv = __builtin_amdgcn_exp2f(s[qt][kt][j]);
;             if (MODE == 1) {
;               int keep;
;               asm("v_bfe_i32 %0, %1, %2, 1" : "=v"(keep) : "v"(kt < 2 ? mlo[qt] : mhi[qt]), "n"((kt & 1) * 16 + j));
;               pv = __int_as_float(__float_as_int(pv) & keep);
;             }
;             s[qt][kt][j] = pv; rs += pv;
;           }
;         rs = xq_sum(rs);
;         lrow[qt] = lrow[qt] * alpha + rs;
;         if (grow) {
; #pragma unroll
;           for (int dt = 0; dt < 8; ++dt) o[qt][dt] *= alpha;
.LBB0_1811:
	v_exp_f32_e32 v165, v136
	v_exp_f32_e32 v167, v137
	v_exp_f32_e32 v138, v138
	v_exp_f32_e32 v139, v139
	v_exp_f32_e32 v140, v140
	v_add_f32_e32 v136, v165, v167
	v_exp_f32_e32 v141, v141
	v_add_f32_e32 v136, v138, v136
	v_exp_f32_e32 v166, v142
	v_add_f32_e32 v136, v139, v136
	v_exp_f32_e32 v217, v143
	v_add_f32_e32 v136, v140, v136
	v_exp_f32_e32 v144, v144
	v_add_f32_e32 v136, v141, v136
	v_exp_f32_e32 v145, v145
	v_add_f32_e32 v136, v166, v136
	v_exp_f32_e32 v142, v146
	v_add_f32_e32 v136, v217, v136
	v_exp_f32_e32 v143, v147
	v_add_f32_e32 v136, v144, v136
	v_exp_f32_e32 v146, v148
	v_add_f32_e32 v136, v145, v136
	v_exp_f32_e32 v147, v149
	v_add_f32_e32 v136, v142, v136
	v_exp_f32_e32 v148, v150
	v_add_f32_e32 v136, v143, v136
	v_exp_f32_e32 v149, v151
	v_add_f32_e32 v136, v146, v136
	v_add_f32_e32 v136, v147, v136
	v_add_f32_e32 v136, v148, v136
	v_add_f32_e32 v136, v149, v136
	v_mov_b32_e32 v137, v136
	s_nop 1
	v_permlane16_swap_b32_e32 v136, v137
	v_add_f32_e32 v136, v136, v137
	v_mov_b32_e32 v137, v136
	s_andn2_b64 vcc, exec, s[0:1]
	s_nop 0
	v_permlane32_swap_b32_e32 v136, v137
	s_cbranch_vccnz .LBB0_1813
	v_pk_mul_f32 v[94:95], v[94:95], v[152:153] op_sel_hi:[1,0]
	v_pk_mul_f32 v[92:93], v[92:93], v[152:153] op_sel_hi:[1,0]
	v_pk_mul_f32 v[98:99], v[98:99], v[152:153] op_sel_hi:[1,0]
	v_pk_mul_f32 v[96:97], v[96:97], v[152:153] op_sel_hi:[1,0]
	v_pk_mul_f32 v[102:103], v[102:103], v[152:153] op_sel_hi:[1,0]
	v_pk_mul_f32 v[100:101], v[100:101], v[152:153] op_sel_hi:[1,0]
	v_pk_mul_f32 v[90:91], v[90:91], v[152:153] op_sel_hi:[1,0]
	v_pk_mul_f32 v[88:89], v[88:89], v[152:153] op_sel_hi:[1,0]
	v_pk_mul_f32 v[74:75], v[74:75], v[152:153] op_sel_hi:[1,0]
	v_pk_mul_f32 v[72:73], v[72:73], v[152:153] op_sel_hi:[1,0]
	v_pk_mul_f32 v[78:79], v[78:79], v[152:153] op_sel_hi:[1,0]
	v_pk_mul_f32 v[76:77], v[76:77], v[152:153] op_sel_hi:[1,0]
	v_pk_mul_f32 v[82:83], v[82:83], v[152:153] op_sel_hi:[1,0]
	v_pk_mul_f32 v[80:81], v[80:81], v[152:153] op_sel_hi:[1,0]
	v_pk_mul_f32 v[86:87], v[86:87], v[152:153] op_sel_hi:[1,0]
	v_pk_mul_f32 v[84:85], v[84:85], v[152:153] op_sel_hi:[1,0]
